# v56 + static s_setprio 2 for wave 0 (the wave that runs the serial gate / channel scans) during the mLSTM and RG-LRU chunk loops
# speedup vs baseline: 1.0240x; 1.0016x over previous
;     for (int w = blockIdx.x; w < 256; w += gridDim.x) {
;         if (w < 128) { if (mask & 1) mlstm_unit(p, smem, w); } else { if (mask & 2) lru_unit(p, smem, w - 128); }
.LBB0_325:
	s_setprio 0
	s_mov_b64 s[74:75], s[90:91]
	v_readlane_b32 s94, v230, 23
	v_readlane_b32 s90, v230, 45
	v_readlane_b32 s95, v230, 24
	v_readlane_b32 s91, v230, 46
	v_readlane_b32 s34, v230, 47
	s_movk_i32 s35, 0x110

; DI void lru_unit(const Params& p, unsigned char* smem, int unit) {
;     ...
;     float br[4], bi[4], sp[4];
; #pragma unroll
;     for (int j = 0; j < 4; ++j) {
;         const int ch = n * 128 + half * 64 + et * 16 + fq * 4 + j;
;         br[j] = p.b_r[ch]; bi[j] = p.b_i[ch];
;         const float l = p.lam[ch];
;         sp[j] = fmaxf(-l, 0.f) + log1pf(__expf(-fabsf(l)));
;     }
.LBB0_336:
	s_or_b64 exec, exec, s[0:1]
	s_mov_b32 s9, 0xbfb8aa3b
	s_waitcnt vmcnt(1)
	v_mul_f32_e64 v72, |v64|, s9
	v_exp_f32_e32 v81, v72
	v_max_f32_e64 v64, -v64, -v64
	v_max_f32_e32 v73, 0, v64
	s_mov_b32 s10, 0x3f2aaaab
	v_add_f32_e32 v110, 1.0, v81
	v_add_f32_e32 v64, -1.0, v110
	v_sub_f32_e32 v72, v64, v110
	v_add_f32_e32 v72, 1.0, v72
	v_sub_f32_e32 v64, v81, v64
	v_add_f32_e32 v111, v64, v72
	v_mul_f32_e64 v64, |v65|, s9
	v_exp_f32_e32 v72, v64
	v_cvt_f64_f32_e32 v[82:83], v110
	v_max_f32_e64 v64, -v65, -v65
	v_frexp_exp_i32_f64_e32 v113, v[82:83]
	v_add_f32_e32 v84, 1.0, v72
	v_add_f32_e32 v65, -1.0, v84
	v_sub_f32_e32 v82, v65, v84
	v_add_f32_e32 v82, 1.0, v82
	v_sub_f32_e32 v65, v72, v65
	v_add_f32_e32 v85, v65, v82
	v_mul_f32_e64 v65, |v66|, s9
	v_exp_f32_e32 v114, v65
	v_cvt_f64_f32_e32 v[82:83], v84
	v_max_f32_e64 v65, -v66, -v66
	v_frexp_exp_i32_f64_e32 v87, v[82:83]
	v_add_f32_e32 v66, 1.0, v114
	v_add_f32_e32 v82, -1.0, v66
	v_sub_f32_e32 v83, v82, v66
	v_add_f32_e32 v83, 1.0, v83
	v_sub_f32_e32 v82, v114, v82
	v_add_f32_e32 v88, v82, v83
	v_frexp_mant_f32_e32 v89, v66
	v_cvt_f64_f32_e32 v[82:83], v66
	v_frexp_exp_i32_f64_e32 v82, v[82:83]
	v_cmp_gt_f32_e32 vcc, s10, v89
	v_frexp_mant_f32_e32 v86, v84
	s_movk_i32 s7, 0x43
	v_subbrev_co_u32_e32 v115, vcc, 0, v82, vcc
	v_cmp_gt_f32_e32 vcc, s10, v86
	s_mov_b32 s6, 0x3ecc95a3
	s_mov_b32 s16, 0x3f2aaada
	v_subbrev_co_u32_e32 v122, vcc, 0, v87, vcc
	v_sub_u32_e32 v83, 0, v122
	v_ldexp_f32 v82, v84, v83
	v_ldexp_f32 v84, v85, v83
	v_sub_u32_e32 v85, 0, v115
	v_ldexp_f32 v83, v66, v85
	v_pk_add_f32 v[86:87], v[82:83], 1.0 op_sel_hi:[1,0]
	v_ldexp_f32 v85, v88, v85
	v_pk_add_f32 v[88:89], v[86:87], -1.0 op_sel_hi:[1,0]
	v_pk_add_f32 v[94:95], v[82:83], -1.0 op_sel_hi:[1,0]
	v_pk_add_f32 v[88:89], v[82:83], v[88:89] neg_lo:[0,1] neg_hi:[0,1]
	v_pk_add_f32 v[96:97], v[94:95], 1.0 op_sel_hi:[1,0]
	v_pk_add_f32 v[88:89], v[84:85], v[88:89]
	v_pk_add_f32 v[82:83], v[82:83], v[96:97] neg_lo:[0,1] neg_hi:[0,1]
	v_pk_add_f32 v[90:91], v[86:87], v[88:89]
	v_pk_add_f32 v[82:83], v[84:85], v[82:83]
	v_rcp_f32_e32 v92, v90
	v_rcp_f32_e32 v93, v91
	v_pk_add_f32 v[84:85], v[94:95], v[82:83]
	v_pk_add_f32 v[86:87], v[90:91], v[86:87] neg_lo:[0,1] neg_hi:[0,1]
	v_pk_add_f32 v[94:95], v[84:85], v[94:95] neg_lo:[0,1] neg_hi:[0,1]
	v_pk_mul_f32 v[96:97], v[84:85], v[92:93]
	v_pk_add_f32 v[86:87], v[88:89], v[86:87] neg_lo:[0,1] neg_hi:[0,1]
	v_pk_mul_f32 v[88:89], v[90:91], v[96:97]
	v_pk_add_f32 v[82:83], v[82:83], v[94:95] neg_lo:[0,1] neg_hi:[0,1]
	v_pk_fma_f32 v[94:95], v[96:97], v[90:91], v[88:89] neg_lo:[0,0,1] neg_hi:[0,0,1]
	s_mov_b32 s20, 0x3f317218
	v_pk_fma_f32 v[94:95], v[96:97], v[86:87], v[94:95]
	s_mov_b32 s22, 0xb102e308
	v_pk_add_f32 v[98:99], v[88:89], v[94:95]
	s_mov_b32 s11, 0x7f800000
	v_pk_add_f32 v[100:101], v[84:85], v[98:99] neg_lo:[0,1] neg_hi:[0,1]
	v_pk_add_f32 v[88:89], v[98:99], v[88:89] neg_lo:[0,1] neg_hi:[0,1]
	v_pk_add_f32 v[84:85], v[84:85], v[100:101] neg_lo:[0,1] neg_hi:[0,1]
	v_cmp_neq_f32_e32 vcc, s11, v72
	v_pk_add_f32 v[84:85], v[84:85], v[98:99] neg_lo:[0,1] neg_hi:[0,1]
	s_mov_b32 s15, 0x33800000
	v_pk_add_f32 v[82:83], v[82:83], v[84:85]
	v_pk_add_f32 v[84:85], v[88:89], v[94:95] neg_lo:[0,1] neg_hi:[0,1]
	v_max_f32_e32 v64, 0, v64
	v_pk_add_f32 v[82:83], v[84:85], v[82:83]
	v_max_f32_e32 v65, 0, v65
	v_pk_add_f32 v[84:85], v[100:101], v[82:83]
	v_frexp_mant_f32_e32 v112, v110
	v_pk_mul_f32 v[88:89], v[92:93], v[84:85]
	v_pk_add_f32 v[100:101], v[100:101], v[84:85] neg_lo:[0,1] neg_hi:[0,1]
	v_pk_mul_f32 v[94:95], v[90:91], v[88:89]
	v_pk_add_f32 v[82:83], v[82:83], v[100:101]
	v_pk_fma_f32 v[90:91], v[88:89], v[90:91], v[94:95] neg_lo:[0,0,1] neg_hi:[0,0,1]
	v_pk_add_f32 v[108:109], v[96:97], v[88:89]
	v_pk_fma_f32 v[86:87], v[88:89], v[86:87], v[90:91]
	v_and_b32_e32 v80, 63, v69
	v_pk_add_f32 v[90:91], v[94:95], v[86:87]
	s_cmp_lt_u32 s13, 16
	v_pk_add_f32 v[102:103], v[84:85], v[90:91] neg_lo:[0,1] neg_hi:[0,1]
	v_pk_add_f32 v[98:99], v[90:91], v[94:95] neg_lo:[0,1] neg_hi:[0,1]
	v_pk_add_f32 v[106:107], v[84:85], v[102:103] neg_lo:[0,1] neg_hi:[0,1]
	v_mov_b32_e32 v84, v91
	v_mov_b32_e32 v94, v95
	v_mov_b32_e32 v95, v103
	v_pk_add_f32 v[106:107], v[106:107], v[90:91] neg_lo:[0,1] neg_hi:[0,1]
	v_pk_add_f32 v[84:85], v[84:85], v[94:95] neg_lo:[0,1] neg_hi:[0,1]
	v_mov_b32_e32 v90, v87
	v_pk_add_f32 v[84:85], v[84:85], v[90:91] neg_lo:[0,1] neg_hi:[0,1]
	v_pk_add_f32 v[98:99], v[98:99], v[86:87] neg_lo:[0,1] neg_hi:[0,1]
	v_mov_b32_e32 v107, v85
	v_pk_add_f32 v[82:83], v[82:83], v[106:107]
	v_mov_b32_e32 v99, v84
	v_pk_add_f32 v[82:83], v[98:99], v[82:83]
	v_pk_add_f32 v[84:85], v[108:109], v[96:97] neg_lo:[0,1] neg_hi:[0,1]
	v_pk_add_f32 v[82:83], v[102:103], v[82:83]
	v_pk_add_f32 v[84:85], v[88:89], v[84:85] neg_lo:[0,1] neg_hi:[0,1]
	v_pk_mul_f32 v[82:83], v[92:93], v[82:83]
	v_mov_b64_e32 v[92:93], s[6:7]
	v_pk_add_f32 v[82:83], v[84:85], v[82:83]
	s_mov_b32 s6, 0x3e9b6dac
	v_pk_add_f32 v[84:85], v[108:109], v[82:83]
	v_cvt_f32_i32_e32 v91, v115
	v_pk_mul_f32 v[88:89], v[84:85], v[84:85]
	v_pk_add_f32 v[86:87], v[84:85], v[108:109] neg_lo:[0,1] neg_hi:[0,1]
	v_pk_fma_f32 v[94:95], v[88:89], s[6:7], v[92:93] op_sel_hi:[1,0,0]
	v_pk_add_f32 v[82:83], v[82:83], v[86:87] neg_lo:[0,1] neg_hi:[0,1]
	v_ldexp_f32 v86, v84, 1
	v_cvt_f32_i32_e32 v90, v122
	v_pk_fma_f32 v[94:95], v[88:89], v[94:95], s[16:17] op_sel_hi:[1,1,0]
	v_ldexp_f32 v87, v85, 1
	v_pk_mul_f32 v[84:85], v[84:85], v[88:89]
	v_ldexp_f32 v82, v82, 1
	v_pk_mul_f32 v[84:85], v[84:85], v[94:95]
	v_pk_mul_f32 v[96:97], v[90:91], s[20:21] op_sel_hi:[1,0]
	v_pk_add_f32 v[88:89], v[86:87], v[84:85]
; DI void lru_unit(const Params& p, unsigned char* smem, int unit) {
;     ...
;     float br[4], bi[4], sp[4];
; #pragma unroll
;     for (int j = 0; j < 4; ++j) {
;         const int ch = n * 128 + half * 64 + et * 16 + fq * 4 + j;
;         br[j] = p.b_r[ch]; bi[j] = p.b_i[ch];
;         const float l = p.lam[ch];
;         sp[j] = fmaxf(-l, 0.f) + log1pf(__expf(-fabsf(l)));
;     }
	v_ldexp_f32 v83, v83, 1
	v_pk_add_f32 v[86:87], v[88:89], v[86:87] neg_lo:[0,1] neg_hi:[0,1]
	v_pk_fma_f32 v[98:99], v[90:91], s[20:21], v[96:97] op_sel_hi:[1,0,1] neg_lo:[0,0,1] neg_hi:[0,0,1]
	v_pk_add_f32 v[84:85], v[84:85], v[86:87] neg_lo:[0,1] neg_hi:[0,1]
	v_pk_fma_f32 v[90:91], v[90:91], s[22:23], v[98:99] op_sel_hi:[1,0,1]
	v_pk_add_f32 v[82:83], v[82:83], v[84:85]
	v_pk_add_f32 v[98:99], v[96:97], v[90:91]
	v_pk_add_f32 v[84:85], v[88:89], v[82:83]
	v_pk_add_f32 v[96:97], v[98:99], v[96:97] neg_lo:[0,1] neg_hi:[0,1]
	v_pk_add_f32 v[86:87], v[84:85], v[88:89] neg_lo:[0,1] neg_hi:[0,1]
	v_pk_add_f32 v[90:91], v[90:91], v[96:97] neg_lo:[0,1] neg_hi:[0,1]
	v_pk_add_f32 v[82:83], v[82:83], v[86:87] neg_lo:[0,1] neg_hi:[0,1]
	v_pk_add_f32 v[86:87], v[98:99], v[84:85]
	v_subrev_u32_e32 v122, 64, v71
	v_pk_add_f32 v[88:89], v[86:87], v[98:99] neg_lo:[0,1] neg_hi:[0,1]
	s_movk_i32 s13, 0x104
	v_pk_add_f32 v[94:95], v[86:87], v[88:89] neg_lo:[0,1] neg_hi:[0,1]
	v_pk_add_f32 v[84:85], v[84:85], v[88:89] neg_lo:[0,1] neg_hi:[0,1]
	v_pk_add_f32 v[94:95], v[98:99], v[94:95] neg_lo:[0,1] neg_hi:[0,1]
	v_pk_add_f32 v[88:89], v[90:91], v[82:83]
	v_pk_add_f32 v[84:85], v[84:85], v[94:95]
	v_pk_add_f32 v[94:95], v[88:89], v[90:91] neg_lo:[0,1] neg_hi:[0,1]
	v_pk_add_f32 v[84:85], v[88:89], v[84:85]
	v_pk_add_f32 v[96:97], v[88:89], v[94:95] neg_lo:[0,1] neg_hi:[0,1]
	v_pk_add_f32 v[88:89], v[86:87], v[84:85]
	v_pk_add_f32 v[90:91], v[90:91], v[96:97] neg_lo:[0,1] neg_hi:[0,1]
	v_pk_add_f32 v[82:83], v[82:83], v[94:95] neg_lo:[0,1] neg_hi:[0,1]
	v_pk_add_f32 v[86:87], v[88:89], v[86:87] neg_lo:[0,1] neg_hi:[0,1]
	v_pk_add_f32 v[82:83], v[82:83], v[90:91]
	v_pk_add_f32 v[84:85], v[84:85], v[86:87] neg_lo:[0,1] neg_hi:[0,1]
	v_add_u32_e32 v128, -16, v71
	v_pk_add_f32 v[82:83], v[82:83], v[84:85]
	v_lshl_or_b32 v71, v116, 1, 1
	v_pk_add_f32 v[82:83], v[88:89], v[82:83]
	v_lshlrev_b32_e32 v123, 9, v116
	v_cndmask_b32_e32 v66, v137, v82, vcc
	v_cmp_neq_f32_e32 vcc, s11, v114
	v_cmp_gt_i32_e64 s[0:1], s7, v120
	v_cmp_gt_i32_e64 s[4:5], s7, v118
	v_cndmask_b32_e32 v82, v137, v83, vcc
	v_cmp_ngt_f32_e32 vcc, -1.0, v114
	s_mov_b32 s18, 0
	v_lshl_add_u32 v146, v80, 2, s83
	v_cndmask_b32_e32 v82, v138, v82, vcc
	v_cmp_ngt_f32_e32 vcc, -1.0, v72
	s_waitcnt lgkmcnt(0)
	s_barrier
	v_cndmask_b32_e32 v66, v138, v66, vcc
	v_cmp_neq_f32_e32 vcc, -1.0, v72
	s_nop 1
	v_cndmask_b32_e32 v66, v135, v66, vcc
	v_cmp_neq_f32_e32 vcc, -1.0, v114
	s_nop 1
	v_cndmask_b32_e32 v82, v135, v82, vcc
	v_cmp_lt_f32_e64 vcc, |v114|, s15
	s_nop 1
	v_cndmask_b32_e32 v83, v82, v114, vcc
	v_cmp_lt_f32_e64 vcc, |v72|, s15
	s_nop 1
	v_cndmask_b32_e32 v82, v66, v72, vcc
	v_mul_f32_e64 v66, |v67|, s9
	v_exp_f32_e32 v108, v66
	v_pk_add_f32 v[106:107], v[64:65], v[82:83]
	v_max_f32_e64 v64, -v67, -v67
	v_max_f32_e32 v72, 0, v64
	v_add_f32_e32 v66, 1.0, v108
	v_add_f32_e32 v64, -1.0, v66
	v_sub_f32_e32 v65, v64, v66
	v_add_f32_e32 v65, 1.0, v65
	v_sub_f32_e32 v64, v108, v64
	v_add_f32_e32 v84, v64, v65
	v_frexp_mant_f32_e32 v67, v66
	v_cvt_f64_f32_e32 v[64:65], v66
	v_frexp_exp_i32_f64_e32 v64, v[64:65]
	v_cmp_gt_f32_e32 vcc, s10, v67
	s_nop 1
	v_subbrev_co_u32_e32 v64, vcc, 0, v64, vcc
	v_cmp_gt_f32_e32 vcc, s10, v112
	v_sub_u32_e32 v85, 0, v64
	v_readlane_b32 s10, v230, 37
	v_subbrev_co_u32_e32 v82, vcc, 0, v113, vcc
	v_sub_u32_e32 v67, 0, v82
	v_cvt_f32_i32_e32 v83, v82
	v_cvt_f32_i32_e32 v82, v64
	v_ldexp_f32 v64, v66, v85
	v_ldexp_f32 v66, v84, v85
	v_ldexp_f32 v65, v110, v67
	v_pk_mul_f32 v[84:85], v[82:83], s[20:21] op_sel_hi:[1,0]
	v_pk_add_f32 v[94:95], v[64:65], 1.0 op_sel_hi:[1,0]
	v_pk_fma_f32 v[86:87], v[82:83], s[20:21], v[84:85] op_sel_hi:[1,0,1] neg_lo:[0,0,1] neg_hi:[0,0,1]
	v_pk_add_f32 v[96:97], v[94:95], -1.0 op_sel_hi:[1,0]
	v_pk_fma_f32 v[82:83], v[82:83], s[22:23], v[86:87] op_sel_hi:[1,0,1]
	v_pk_add_f32 v[86:87], v[64:65], -1.0 op_sel_hi:[1,0]
	v_ldexp_f32 v67, v111, v67
	v_pk_add_f32 v[88:89], v[86:87], 1.0 op_sel_hi:[1,0]
	v_cmp_neq_f32_e32 vcc, s11, v108
	v_pk_add_f32 v[88:89], v[64:65], v[88:89] neg_lo:[0,1] neg_hi:[0,1]
	v_pk_add_f32 v[64:65], v[64:65], v[96:97] neg_lo:[0,1] neg_hi:[0,1]
	v_pk_add_f32 v[88:89], v[66:67], v[88:89]
	v_pk_add_f32 v[64:65], v[66:67], v[64:65]
	v_pk_add_f32 v[90:91], v[86:87], v[88:89]
	v_pk_add_f32 v[66:67], v[94:95], v[64:65]
	v_pk_add_f32 v[86:87], v[90:91], v[86:87] neg_lo:[0,1] neg_hi:[0,1]
	v_rcp_f32_e32 v97, v67
	v_rcp_f32_e32 v96, v66
	v_pk_add_f32 v[86:87], v[88:89], v[86:87] neg_lo:[0,1] neg_hi:[0,1]
	v_pk_add_f32 v[88:89], v[66:67], v[94:95] neg_lo:[0,1] neg_hi:[0,1]
	s_nop 0
	v_pk_add_f32 v[64:65], v[64:65], v[88:89] neg_lo:[0,1] neg_hi:[0,1]
	v_pk_mul_f32 v[88:89], v[90:91], v[96:97]
	s_nop 0
	v_pk_mul_f32 v[94:95], v[66:67], v[88:89]
	s_nop 0
	v_pk_fma_f32 v[98:99], v[88:89], v[66:67], v[94:95] neg_lo:[0,0,1] neg_hi:[0,0,1]
	s_nop 0
	v_pk_fma_f32 v[98:99], v[88:89], v[64:65], v[98:99]
	s_nop 0
	v_pk_add_f32 v[100:101], v[94:95], v[98:99]
	s_nop 0
	v_pk_add_f32 v[102:103], v[90:91], v[100:101] neg_lo:[0,1] neg_hi:[0,1]
	v_pk_add_f32 v[94:95], v[100:101], v[94:95] neg_lo:[0,1] neg_hi:[0,1]
	v_pk_add_f32 v[90:91], v[90:91], v[102:103] neg_lo:[0,1] neg_hi:[0,1]
	s_nop 0
	v_pk_add_f32 v[90:91], v[90:91], v[100:101] neg_lo:[0,1] neg_hi:[0,1]
	s_nop 0
	v_pk_add_f32 v[86:87], v[86:87], v[90:91]
	v_pk_add_f32 v[90:91], v[94:95], v[98:99] neg_lo:[0,1] neg_hi:[0,1]
	s_nop 0
	v_pk_add_f32 v[86:87], v[90:91], v[86:87]
	s_nop 0
	v_pk_add_f32 v[90:91], v[102:103], v[86:87]
	s_nop 0
	v_pk_mul_f32 v[94:95], v[96:97], v[90:91]
	v_pk_add_f32 v[102:103], v[102:103], v[90:91] neg_lo:[0,1] neg_hi:[0,1]
	v_pk_mul_f32 v[98:99], v[66:67], v[94:95]
; DI void lru_unit(const Params& p, unsigned char* smem, int unit) {
;     ...
;     float br[4], bi[4], sp[4];
; #pragma unroll
;     for (int j = 0; j < 4; ++j) {
;         const int ch = n * 128 + half * 64 + et * 16 + fq * 4 + j;
;         br[j] = p.b_r[ch]; bi[j] = p.b_i[ch];
;         const float l = p.lam[ch];
;         sp[j] = fmaxf(-l, 0.f) + log1pf(__expf(-fabsf(l)));
;     }
;     float hstate = 0.f;
;     u32x4 rr_[3], rg_;
;     auto issue_loads = [&](int c) __attribute__((always_inline)) {
;         const int t0 = c == 0 ? 0 : 16 + (c - 1) * 64;
;         {
;             const int t = tid >> 3, nvc = c == 0 ? 16 : 64;
;             const size_t row = (size_t)((c == 0 ? MR : b * 4096 + (c - 1) * 64) + (t < nvc ? t : 0));
;             rg_ = *(const u32x4*)(OG + row * 2048 + 1024 + n * 128 + half * 64 + (tid & 7) * 8);
;         }
; #pragma unroll
;         for (int i = 0; i < 3; ++i) {
;             const int vid = tid + 512 * i, ri = vid >> 4, part = vid & 15;
;             const int tt = t0 - 3 + ri;
;             u32x4 v = (u32x4){0u, 0u, 0u, 0u};
;             if (ri < 67 && tt >= 0 && tt < TSEQ) {
;                 const size_t row = tt < 16 ? (size_t)(MR + tt) : (size_t)(b * 4096 + tt - 16);
;                 v = *(const u32x4*)(T1 + row * 4096 + 3072 + n * 128 + part * 8);
;             }
;             rr_[i] = v;
;         }
;     };
;     issue_loads(0);
;     __syncthreads();
	v_pk_add_f32 v[86:87], v[86:87], v[102:103]
	v_pk_fma_f32 v[66:67], v[94:95], v[66:67], v[98:99] neg_lo:[0,0,1] neg_hi:[0,0,1]
	s_nop 0
	v_pk_fma_f32 v[64:65], v[94:95], v[64:65], v[66:67]
	s_nop 0
	v_pk_add_f32 v[66:67], v[98:99], v[64:65]
	s_nop 0
	v_pk_add_f32 v[100:101], v[90:91], v[66:67] neg_lo:[0,1] neg_hi:[0,1]
	v_pk_add_f32 v[98:99], v[66:67], v[98:99] neg_lo:[0,1] neg_hi:[0,1]
	v_pk_add_f32 v[90:91], v[90:91], v[100:101] neg_lo:[0,1] neg_hi:[0,1]
	v_pk_add_f32 v[64:65], v[98:99], v[64:65] neg_lo:[0,1] neg_hi:[0,1]
	v_pk_add_f32 v[66:67], v[90:91], v[66:67] neg_lo:[0,1] neg_hi:[0,1]
	s_nop 0
	v_pk_add_f32 v[66:67], v[86:87], v[66:67]
	s_nop 0
	v_pk_add_f32 v[64:65], v[64:65], v[66:67]
	v_pk_add_f32 v[66:67], v[88:89], v[94:95]
	v_pk_add_f32 v[64:65], v[100:101], v[64:65]
	v_pk_add_f32 v[86:87], v[66:67], v[88:89] neg_lo:[0,1] neg_hi:[0,1]
	v_pk_mul_f32 v[64:65], v[96:97], v[64:65]
	v_pk_add_f32 v[86:87], v[94:95], v[86:87] neg_lo:[0,1] neg_hi:[0,1]
	s_nop 0
	v_pk_add_f32 v[64:65], v[86:87], v[64:65]
	s_nop 0
	v_pk_add_f32 v[86:87], v[66:67], v[64:65]
	s_nop 0
	v_pk_mul_f32 v[88:89], v[86:87], v[86:87]
	v_pk_add_f32 v[66:67], v[86:87], v[66:67] neg_lo:[0,1] neg_hi:[0,1]
	v_pk_fma_f32 v[90:91], v[88:89], s[6:7], v[92:93] op_sel_hi:[1,0,0]
	v_pk_add_f32 v[64:65], v[64:65], v[66:67] neg_lo:[0,1] neg_hi:[0,1]
	v_ldexp_f32 v67, v87, 1
	v_pk_fma_f32 v[90:91], v[88:89], v[90:91], s[16:17] op_sel_hi:[1,1,0]
	v_ldexp_f32 v66, v86, 1
	v_pk_mul_f32 v[86:87], v[86:87], v[88:89]
	v_ldexp_f32 v65, v65, 1
	v_pk_mul_f32 v[86:87], v[86:87], v[90:91]
	v_ldexp_f32 v64, v64, 1
	v_pk_add_f32 v[88:89], v[66:67], v[86:87]
	s_cselect_b64 s[16:17], -1, 0
	v_pk_add_f32 v[66:67], v[88:89], v[66:67] neg_lo:[0,1] neg_hi:[0,1]
	v_mov_b32_e32 v97, v89
	v_pk_add_f32 v[66:67], v[86:87], v[66:67] neg_lo:[0,1] neg_hi:[0,1]
	s_lshl_b32 s92, s14, 1
	v_pk_add_f32 v[64:65], v[64:65], v[66:67]
	v_pk_add_f32 v[66:67], v[84:85], v[82:83]
	v_pk_add_f32 v[86:87], v[88:89], v[64:65]
	v_pk_add_f32 v[84:85], v[66:67], v[84:85] neg_lo:[0,1] neg_hi:[0,1]
	v_pk_add_f32 v[90:91], v[66:67], v[86:87]
	v_mov_b32_e32 v95, v87
	v_pk_add_f32 v[92:93], v[90:91], v[66:67] neg_lo:[0,1] neg_hi:[0,1]
	v_mov_b32_e32 v94, v90
	v_mov_b32_e32 v96, v92
	v_pk_add_f32 v[94:95], v[94:95], v[96:97] neg_lo:[0,1] neg_hi:[0,1]
	v_mov_b32_e32 v96, v66
	v_mov_b32_e32 v97, v65
	v_pk_add_f32 v[92:93], v[86:87], v[92:93] neg_lo:[0,1] neg_hi:[0,1]
	v_pk_add_f32 v[82:83], v[82:83], v[84:85] neg_lo:[0,1] neg_hi:[0,1]
	v_pk_add_f32 v[94:95], v[96:97], v[94:95] neg_lo:[0,1] neg_hi:[0,1]
	v_mov_b32_e32 v93, v83
	v_pk_add_f32 v[84:85], v[92:93], v[94:95]
	v_mov_b32_e32 v92, v86
	v_mov_b32_e32 v93, v91
	v_mov_b32_e32 v89, v67
	v_pk_add_f32 v[88:89], v[92:93], v[88:89] neg_lo:[0,1] neg_hi:[0,1]
	v_mov_b32_e32 v65, v87
	v_pk_add_f32 v[92:93], v[90:91], v[88:89] neg_lo:[0,1] neg_hi:[0,1]
	v_pk_add_f32 v[64:65], v[64:65], v[88:89] neg_lo:[0,1] neg_hi:[0,1]
	v_pk_add_f32 v[66:67], v[66:67], v[92:93] neg_lo:[0,1] neg_hi:[0,1]
	v_mov_b32_e32 v87, v85
	v_mov_b32_e32 v66, v82
	v_pk_add_f32 v[66:67], v[64:65], v[66:67]
	v_mov_b32_e32 v65, v95
	v_mov_b32_e32 v86, v66
	v_pk_add_f32 v[88:89], v[86:87], v[82:83] neg_lo:[0,1] neg_hi:[0,1]
	v_pk_add_f32 v[66:67], v[84:85], v[66:67]
	v_pk_add_f32 v[86:87], v[86:87], v[88:89] neg_lo:[0,1] neg_hi:[0,1]
	v_pk_add_f32 v[64:65], v[64:65], v[88:89] neg_lo:[0,1] neg_hi:[0,1]
	v_pk_add_f32 v[82:83], v[82:83], v[86:87] neg_lo:[0,1] neg_hi:[0,1]
	v_cmp_gt_i32_e64 s[6:7], s7, v116
	v_pk_add_f32 v[64:65], v[64:65], v[82:83]
	v_pk_add_f32 v[82:83], v[90:91], v[66:67]
	s_nop 0
	v_pk_add_f32 v[84:85], v[82:83], v[90:91] neg_lo:[0,1] neg_hi:[0,1]
	s_nop 0
	v_pk_add_f32 v[66:67], v[66:67], v[84:85] neg_lo:[0,1] neg_hi:[0,1]
	s_nop 0
	v_pk_add_f32 v[64:65], v[64:65], v[66:67]
	v_lshrrev_b32_e32 v67, 3, v75
	v_pk_add_f32 v[64:65], v[82:83], v[64:65]
	v_cmp_eq_u32_e64 s[8:9], s8, v67
	v_cndmask_b32_e32 v64, v137, v64, vcc
	v_cmp_neq_f32_e32 vcc, s11, v81
	v_lshlrev_b32_e32 v67, 2, v79
	v_add_u32_e32 v124, s10, v67
	v_cndmask_b32_e32 v65, v137, v65, vcc
	v_cmp_ngt_f32_e32 vcc, -1.0, v81
	v_mul_lo_u32 v79, v71, s35
	s_nop 0
	v_cndmask_b32_e32 v65, v138, v65, vcc
	v_cmp_ngt_f32_e32 vcc, -1.0, v108
	s_nop 1
	v_cndmask_b32_e32 v64, v138, v64, vcc
	v_cmp_neq_f32_e32 vcc, -1.0, v108
	s_nop 1
	v_cndmask_b32_e32 v64, v135, v64, vcc
	v_cmp_neq_f32_e32 vcc, -1.0, v81
	s_nop 1
	v_cndmask_b32_e32 v65, v135, v65, vcc
	v_cmp_lt_f32_e64 vcc, |v81|, s15
	s_nop 1
	v_cndmask_b32_e32 v65, v65, v81, vcc
	v_cmp_lt_f32_e64 vcc, |v108|, s15
	v_lshlrev_b32_e32 v81, 8, v71
	v_readlane_b32 s15, v230, 38
	v_cndmask_b32_e32 v64, v64, v108, vcc
	v_pk_add_f32 v[108:109], v[72:73], v[64:65]
	v_or_b32_e32 v72, v77, v75
	v_mul_u32_u24_e32 v72, 0x110, v72
	v_lshlrev_b32_e32 v73, 4, v74
	v_add3_u32 v125, 0, v72, v73
	v_lshlrev_b32_e32 v73, 2, v77
	v_lshlrev_b32_e32 v74, 2, v78
	v_cmp_gt_i32_e32 vcc, 64, v117
	v_and_b32_e32 v72, 48, v69
	v_add3_u32 v126, s10, v73, v74
	v_cmp_gt_u32_e64 s[10:11], 64, v69
	v_cndmask_b32_e32 v69, 0, v117, vcc
	v_add_u32_e32 v127, v122, v69
	v_mul_lo_u32 v69, v117, s13
	s_movk_i32 s13, 0x220
	v_mul_lo_u32 v78, v116, s13
	s_movk_i32 s13, 0xffe0
	v_and_or_b32 v71, v117, s13, v75
	v_lshlrev_b32_e32 v65, 4, v75
	v_mul_lo_u32 v75, v71, s35
	v_lshlrev_b32_e32 v129, 8, v71
	v_lshl_add_u32 v71, v71, 6, v71
	s_add_u32 s13, s74, s92
	v_add_lshl_u32 v71, v76, v71, 2
	s_addc_u32 s14, s75, 0
	s_lshl_b32 s12, s12, 1
	v_add_u32_e32 v130, s83, v71
	v_add_u32_e32 v131, s15, v71
	v_add_u32_e32 v82, 0x1040, v71
	v_add_u32_e32 v71, 0x1048, v71
	s_add_u32 s12, s13, s12
	v_add_u32_e32 v64, 0, v123
	v_add_u32_e32 v66, 0, v65
	v_add_u32_e32 v72, 0, v72
	v_add_u32_e32 v67, s15, v67
	v_lshlrev_b32_e32 v73, 8, v116
	v_lshlrev_b32_e32 v74, 8, v118
	v_lshlrev_b32_e32 v77, 8, v120
	v_or_b32_e32 v76, 0x1000, v129
	v_add_u32_e32 v144, s83, v71
	v_add_u32_e32 v145, s15, v71
	s_addc_u32 s13, s14, 0
	v_mov_b32_e32 v71, v105
	v_add_u32_e32 v132, 4, v131
	v_add_u32_e32 v133, 12, v131
	v_add_u32_e32 v142, s83, v82
	v_add_u32_e32 v143, s15, v82
	v_pk_mov_b32 v[110:111], v[106:107], v[108:109] op_sel:[1,0]
	v_pk_mov_b32 v[112:113], v[108:109], v[106:107] op_sel:[1,0]
	v_lshl_add_u64 v[114:115], s[12:13], 0, v[70:71]
	v_add_u32_e32 v147, v68, v73
	v_add_u32_e32 v148, v68, v74
	v_add_u32_e32 v149, v68, v77
	v_add_u32_e32 v150, v64, v65
	v_add_u32_e32 v151, v66, v78
	v_add_u32_e32 v152, v66, v79
	v_add_u32_e32 v153, v124, v81
	v_add_u32_e32 v154, v72, v75
	v_add_u32_e32 v155, v126, v76
	v_add_u32_e32 v156, v67, v69
	v_lshrrev_b32_e32 v212, 6, v178
	s_nop 0
	v_readfirstlane_b32 s98, v212
	s_nop 3
	s_cmp_lg_u32 s98, 0
	s_cbranch_scc1 .Lprio_lru
	s_setprio 2
.Lprio_lru:
	s_waitcnt vmcnt(0)
	s_branch .LBB0_338

; DI void lru_unit(const Params& p, unsigned char* smem, int unit) {
;     ...
;     }
;     __syncthreads();
.LBB0_361:
	s_setprio 0
	s_mov_b64 s[0:1], 0
	s_barrier

; DI void mlstm_unit(const Params& p, unsigned char* smem, int unit) {
;     ...
;     f32x4 accC[2][4];
; #pragma unroll
;     for (int a = 0; a < 2; ++a)
; #pragma unroll
;         for (int v = 0; v < 4; ++v) accC[a][v] = (f32x4){0.f, 0.f, 0.f, 0.f};
;     if (tid < 256) sN[tid] = 0.f;
;     float m_prev = 0.f;
;     const int ti = wid >> 1, pi = (wid & 1) * 2;
;     u32x4 rq[4], rk[4], rv; float rli = 0.f, rlf = 0.f; u32x2 rog[2];
;     auto issue_loads = [&](int c) __attribute__((always_inline)) {
;         const int base = c == 0 ? MR : b * 4096 + (c - 1) * 64;
;         const int nv = c == 0 ? 16 : 64;
; #pragma unroll
;         for (int i = 0; i < 4; ++i) {
;             const int vid = tid + 512 * i, s = vid >> 5, kv = vid & 31;
;             const size_t row = (size_t)(base + (s < nv ? s : nv - 1));
;             rq[i] = *(const u32x4*)(T1 + row * 4096 + h * 256 + kv * 8);
;             rk[i] = *(const u32x4*)(T1 + row * 4096 + 1024 + h * 256 + kv * 8);
;         }
;         {
;             const int s = lane, vv = wid;
;             const size_t row = (size_t)(base + (s < nv ? s : nv - 1));
;             rv = *(const u32x4*)(T1 + row * 4096 + 2048 + h * 256 + sl * 64 + vv * 8);
;         }
;         if (wid == 0) {
;             const bool ok = lane < nv;
;             const int row = base + (ok ? lane : 0);
;             rli = ok ? LI[row * 4 + h] : -1e30f;
;             rlf = ok ? LF[row * 4 + h] : 0.f;
;         }
;         {
;             const int t = ti * 16 + fr;
;             const size_t row = (size_t)(base + (t < nv ? t : 0));
; #pragma unroll
;             for (int x = 0; x < 2; ++x) rog[x] = *(const u32x2*)(OG + row * 2048 + h * 256 + sl * 64 + (pi + x) * 16 + fq * 4);
;         }
;     };
;     auto gate_scan = [&](float* gb) __attribute__((always_inline)) {
;         const float bb = wave_scan_add(rlf);
;         const float g = rli - bb;
;         const float cm = wave_scan_max(g);
;         const float Mt = fmaxf(m_prev, cm);
;         const float M63 = __builtin_bit_cast(float, __builtin_amdgcn_readlane(__builtin_bit_cast(int, Mt), 63));
;         const float b63 = __builtin_bit_cast(float, __builtin_amdgcn_readlane(__builtin_bit_cast(int, bb), 63));
;         gb[lane] = g; gb[64 + lane] = Mt; gb[128 + lane] = __expf(m_prev - Mt); gb[192 + lane] = __expf(-(bb + Mt)); gb[256 + lane] = __expf(g - M63);
.LBB0_373:
	s_or_b64 exec, exec, s[8:9]
	v_ashrrev_i32_e32 v60, 3, v42
	v_and_b32_e32 v61, 7, v42
	v_mul_lo_u32 v62, v60, s85
	v_lshlrev_b32_e32 v63, 6, v61
	v_add3_u32 v151, 0, v62, v63
	v_and_b32_e32 v63, 64, v141
	v_xor_b32_e32 v62, 1, v141
	v_add_u32_e32 v63, 64, v63
	s_lshl_b32 s8, s84, 2
	v_cmp_lt_i32_e32 vcc, v62, v63
	s_mov_b64 s[90:91], s[74:75]
	s_and_b32 s86, s84, 0xfffff000
	s_and_b32 s39, s8, 0xffffc000
	s_lshr_b32 s74, s2, 2
	v_cndmask_b32_e32 v62, v141, v62, vcc
	s_cmp_lt_u32 s2, 16
	s_mov_b64 s[8:9], s[90:91]
	v_lshlrev_b32_e32 v153, 2, v62
	v_xor_b32_e32 v62, 2, v141
	s_cselect_b64 s[94:95], -1, 0
	s_add_u32 s8, s8, s92
	v_readlane_b32 s14, v230, 41
	v_cmp_lt_i32_e32 vcc, v62, v63
	s_addc_u32 s9, s9, 0
	v_and_b32_e32 v51, 0xff, v42
	v_mov_b32_e32 v53, s14
	s_movk_i32 s72, 0x90
	v_cndmask_b32_e32 v62, v141, v62, vcc
	s_add_u32 s76, s8, s38
	v_lshlrev_b32_e32 v55, 1, v51
	v_mad_u32_u24 v51, v51, s72, v53
	v_mul_lo_u32 v53, v144, s85
	v_and_b32_e32 v58, 48, v42
	v_lshlrev_b32_e32 v154, 2, v62
	v_xor_b32_e32 v62, 4, v141
	v_add_u32_e32 v54, 0, v36
	s_addc_u32 s77, s9, 0
	v_add_u32_e32 v57, 0, v53
	v_lshlrev_b32_e32 v53, 2, v144
	s_add_i32 s13, 0, 0x26400
	v_cmp_lt_i32_e32 vcc, v62, v63
	v_readlane_b32 s15, v230, 44
	v_add_u32_e32 v63, s14, v58
	s_lshl_b32 s12, s12, 2
	v_readlane_b32 s14, v230, 35
	v_add_u32_e32 v156, s15, v53
	v_lshl_add_u32 v157, v60, 2, s15
	s_add_u32 s42, s14, s12
	v_mad_u64_u32 v[110:111], s[14:15], v43, s85, v[54:55]
	v_mad_u64_u32 v[112:113], s[14:15], v45, s85, v[54:55]
	v_mad_u64_u32 v[114:115], s[14:15], v46, s85, v[54:55]
	v_mad_u64_u32 v[116:117], s[14:15], v47, s85, v[54:55]
	v_lshlrev_b32_e32 v146, 4, v49
	v_lshlrev_b32_e32 v147, 2, v50
	v_cndmask_b32_e32 v62, v141, v62, vcc
	s_movk_i32 s14, 0x480
	v_lshlrev_b32_e32 v41, 1, v142
	v_lshlrev_b32_e32 v155, 2, v62
	v_lshl_or_b32 v62, v44, 5, v37
	v_min_i32_e32 v64, 63, v43
	v_mul_lo_u32 v44, v44, s14
	v_and_b32_e32 v160, -8, v43
	v_or_b32_e32 v43, v146, v147
	v_add3_u32 v111, s33, v41, v44
	v_add3_u32 v113, s33, v44, v41
	v_cmp_gt_i32_e64 s[16:17], v43, v144
	v_cmp_gt_i32_e64 s[18:19], v144, v43
	v_or_b32_e32 v44, 3, v43
	v_or_b32_e32 v43, 2, v43
	v_cmp_gt_i32_e64 s[22:23], v43, v144
	v_or_b32_e32 v43, 1, v49
	v_add_u32_e32 v56, 0, v55
	v_mul_lo_u32 v41, v160, s85
	v_and_b32_e32 v164, -8, v45
	v_lshlrev_b32_e32 v118, 4, v43
	v_min_i32_e32 v65, 63, v45
	v_readlane_b32 s12, v230, 36
	v_add_u32_e32 v161, v56, v41
	v_add3_u32 v162, 0, v41, v55
	v_mul_lo_u32 v41, v164, s85
	v_and_b32_e32 v168, -8, v46
	v_or_b32_e32 v45, v118, v147
	v_min_i32_e32 v66, 63, v46
	s_addc_u32 s43, s12, 0
	v_add_u32_e32 v165, v56, v41
	v_add3_u32 v166, 0, v41, v55
	v_mul_lo_u32 v41, v168, s85
	v_and_b32_e32 v172, -8, v47
	v_or_b32_e32 v46, 3, v45
	v_mul_lo_u32 v59, v144, s72
	v_mul_lo_u32 v60, v42, s72
	v_add_u32_e32 v169, v56, v41
	v_add3_u32 v170, 0, v41, v55
	v_mul_lo_u32 v41, v172, s85
	v_cmp_gt_i32_e64 s[26:27], v45, v144
	v_cmp_gt_i32_e64 s[28:29], v144, v45
	v_or_b32_e32 v45, 2, v45
	v_cmp_gt_i32_e64 s[30:31], v46, v144
	v_mul_lo_u32 v46, v62, s72
	s_add_u32 s72, s66, s92
	v_and_b32_e32 v39, 0xffffffc0, v42
	v_readlane_b32 s8, v230, 42
	v_lshl_add_u32 v158, v42, 2, s13
	v_mul_u32_u24_e32 v42, 0x210, v37
	v_add_u32_e32 v173, v56, v41
	v_add3_u32 v174, 0, v41, v55
	v_or_b32_e32 v41, v146, v37
	v_lshlrev_b32_e32 v104, 1, v146
	v_lshlrev_b32_e32 v181, 8, v43
	v_lshlrev_b32_e32 v182, 5, v43
	v_or_b32_e32 v43, v118, v37
	v_cmp_gt_i32_e64 s[34:35], v45, v144
	v_mul_u32_u24_e32 v45, 0x90, v37
	s_addc_u32 s73, s67, 0
	v_mov_b32_e32 v37, v105
	v_lshlrev_b32_e32 v52, 1, v147
	v_add_u32_e32 v148, s8, v53
	v_mov_b32_e32 v53, v105
	v_lshl_add_u64 v[120:121], s[72:73], 0, v[36:37]
	v_lshl_add_u64 v[36:37], s[76:77], 0, v[104:105]
	v_readlane_b32 s10, v230, 40
	v_readlane_b32 s11, v230, 43
	v_cmp_gt_i32_e32 vcc, 64, v144
	v_lshl_add_u64 v[122:123], v[36:37], 0, v[52:53]
	v_lshl_or_b32 v36, v142, 2, s39
	v_add3_u32 v39, s10, v39, v52
	v_add_u32_e32 v149, 0, v58
	v_add3_u32 v150, s11, v59, v52
	v_add_u32_e32 v59, s10, v58
	v_lshl_add_u32 v152, v61, 7, s13
	v_cmp_eq_u32_e64 s[10:11], 0, v61
	v_lshl_add_u32 v50, v50, 4, s33
	v_add_u32_e32 v61, s33, v58
	v_min_i32_e32 v67, 63, v47
	v_cndmask_b32_e32 v68, 0, v144, vcc
	v_mul_u32_u24_e32 v177, 0x210, v41
	v_cmp_gt_i32_e64 s[20:21], v44, v144
	v_mul_u32_u24_e32 v44, 0x210, v43
	v_mul_u32_u24_e32 v41, 0x90, v41
	v_mul_u32_u24_e32 v43, 0x90, v43
	v_and_or_b32 v124, s74, 3, v36
	v_mov_b32_e32 v36, 0
	v_add_u32_e32 v37, 0, v60
	s_mov_b32 s96, 1
	v_cmp_gt_u32_e64 s[8:9], 16, v142
	s_mov_b32 s97, 0
	v_lshl_add_u64 v[108:109], s[76:77], 0, v[52:53]
	v_cmp_eq_u32_e64 s[12:13], 0, v142
	v_add_u32_e32 v115, 0x120, v111
	v_add_u32_e32 v117, 0x240, v111
	v_add_u32_e32 v159, 0x360, v111
	v_lshl_add_u32 v163, v160, 1, v51
	v_lshl_add_u32 v167, v164, 1, v51
	v_lshl_add_u32 v171, v168, 1, v51
	v_lshl_add_u32 v176, v172, 1, v51
	v_cmp_le_i32_e64 s[14:15], v49, v48
	v_lshlrev_b32_e32 v179, 8, v49
	v_add_u32_e32 v180, v150, v104
	v_cmp_ge_i32_e64 s[24:25], v49, v48
	v_add_u32_e32 v183, s86, v68
	v_or_b32_e32 v184, s86, v142
	v_add_u32_e32 v185, s86, v67
	v_add_u32_e32 v186, s86, v66
	v_add_u32_e32 v187, s86, v65
	v_add_u32_e32 v188, s86, v64
	v_add_u32_e32 v189, v39, v42
	v_add_u32_e32 v190, v57, v58
	v_add_u32_e32 v191, v150, v40
	v_add_u32_e32 v192, v149, v44
	v_add_u32_e32 v193, v59, v177
	v_add_u32_e32 v194, v50, v41
	v_add_u32_e32 v195, v150, v38
	v_add_u32_e32 v196, v50, v43
	v_add_u32_e32 v197, v61, v45
	v_add_u32_e32 v198, v63, v46
	v_add_u32_e32 v199, 0x18c00, v37
	v_mov_b32_e32 v37, v36
	v_mov_b32_e32 v38, v36
	v_mov_b32_e32 v39, v36
	v_mov_b32_e32 v40, v36
	v_mov_b32_e32 v41, v36
	v_mov_b32_e32 v42, v36
	v_mov_b32_e32 v43, v36
	v_mov_b32_e32 v44, v36
	v_mov_b32_e32 v45, v36
	v_mov_b32_e32 v46, v36
	v_mov_b32_e32 v47, v36
	v_mov_b32_e32 v64, v36
	v_mov_b32_e32 v65, v36
	v_mov_b32_e32 v66, v36
	v_mov_b32_e32 v67, v36
	v_mov_b32_e32 v48, v36
	v_mov_b32_e32 v49, v36
	v_mov_b32_e32 v50, v36
	v_mov_b32_e32 v51, v36
	v_mov_b32_e32 v52, v36
	v_mov_b32_e32 v53, v36
	v_mov_b32_e32 v54, v36
	v_mov_b32_e32 v55, v36
	v_mov_b32_e32 v56, v36
	v_mov_b32_e32 v57, v36
	v_mov_b32_e32 v58, v36
	v_mov_b32_e32 v59, v36
	v_mov_b32_e32 v60, v36
	v_mov_b32_e32 v61, v36
	v_mov_b32_e32 v62, v36
	v_mov_b32_e32 v63, v36
	v_lshrrev_b32_e32 v212, 6, v178
	s_nop 0
	v_readfirstlane_b32 s98, v212
	s_nop 3
	s_cmp_lg_u32 s98, 0
	s_cbranch_scc1 .Lprio_ml
	s_setprio 2
.Lprio_ml:
	s_waitcnt lgkmcnt(0)
	s_barrier
	s_branch .LBB0_376
